# out-projection K loops: next-step loads issued right after each staging ds_write (before the second barrier), global instead of flat loads
# speedup vs baseline: 1.0150x; 1.0104x over previous
.LBB0_1031:
	s_ashr_i32 s3, s2, 31
	s_lshl_b64 s[0:1], s[2:3], 16
	s_lshl_b64 s[36:37], s[2:3], 17
	s_add_u32 s36, s27, s36
	s_addc_u32 s37, s29, s37
	v_lshl_add_u64 v[0:1], s[36:37], 0, v[184:185]
	v_lshl_add_u64 v[190:191], v[0:1], 0, v[186:187]
	v_mov_b32_e32 v213, v204
	v_add_co_u32_e32 v0, vcc, s35, v190
	v_lshl_add_u64 v[192:193], v[190:191], 0, s[6:7]
	s_nop 0
	v_addc_co_u32_e32 v1, vcc, 0, v191, vcc
	global_load_dwordx4 v[70:73], v[190:191], off
	global_load_dwordx4 v[74:77], v[0:1], off
	global_load_dwordx4 v[98:101], v[112:113], off
	global_load_dwordx4 v[78:81], v[114:115], off
	global_load_dwordx4 v[82:85], v[116:117], off
	global_load_dwordx4 v[86:89], v[118:119], off
	global_load_dwordx4 v[90:93], v[120:121], off
	global_load_dwordx4 v[94:97], v[122:123], off
	global_load_dwordx4 v[102:105], v[124:125], off
	global_load_dwordx4 v[106:109], v[126:127], off
	v_mov_b64_e32 v[194:195], v[176:177]
	s_mov_b32 s3, 0
	v_mov_b32_e32 v0, 0
	v_mov_b32_e32 v1, v111
	v_mov_b32_e32 v2, v111
	v_mov_b32_e32 v3, v111
	v_mov_b32_e32 v4, v111
	v_mov_b32_e32 v5, v111
	v_mov_b32_e32 v6, v111
	v_mov_b32_e32 v7, v111
	v_mov_b32_e32 v8, v111
	v_mov_b32_e32 v9, v111
	v_mov_b32_e32 v10, v111
	v_mov_b32_e32 v11, v111
	v_mov_b32_e32 v12, v111
	v_mov_b32_e32 v13, v111
	v_mov_b32_e32 v14, v111
	v_mov_b32_e32 v15, v111
	v_mov_b32_e32 v16, 0
	v_mov_b32_e32 v17, v111
	v_mov_b32_e32 v18, v111
	v_mov_b32_e32 v19, v111
	v_mov_b32_e32 v20, v111
	v_mov_b32_e32 v21, v111
	v_mov_b32_e32 v22, v111
	v_mov_b32_e32 v23, v111
	v_mov_b32_e32 v24, v111
	v_mov_b32_e32 v25, v111
	v_mov_b32_e32 v26, v111
	v_mov_b32_e32 v27, v111
	v_mov_b32_e32 v28, v111
	v_mov_b32_e32 v29, v111
	v_mov_b32_e32 v30, v111
	v_mov_b32_e32 v31, v111
	v_mov_b32_e32 v32, 0
	v_mov_b32_e32 v33, v111
	v_mov_b32_e32 v34, v111
	v_mov_b32_e32 v35, v111
	v_mov_b32_e32 v36, v111
	v_mov_b32_e32 v37, v111
	v_mov_b32_e32 v38, v111
	v_mov_b32_e32 v39, v111
	v_mov_b32_e32 v40, v111
	v_mov_b32_e32 v41, v111
	v_mov_b32_e32 v42, v111
	v_mov_b32_e32 v43, v111
	v_mov_b32_e32 v44, v111
	v_mov_b32_e32 v45, v111
	v_mov_b32_e32 v46, v111
	v_mov_b32_e32 v47, v111
	v_mov_b32_e32 v48, 0
	v_mov_b32_e32 v49, v111
	v_mov_b32_e32 v50, v111
	v_mov_b32_e32 v51, v111
	v_mov_b32_e32 v52, v111
	v_mov_b32_e32 v53, v111
	v_mov_b32_e32 v54, v111
	v_mov_b32_e32 v55, v111
	v_mov_b32_e32 v56, v111
	v_mov_b32_e32 v57, v111
	v_mov_b32_e32 v58, v111
	v_mov_b32_e32 v59, v111
	v_mov_b32_e32 v60, v111
	v_mov_b32_e32 v61, v111
	v_mov_b32_e32 v62, v111
	v_mov_b32_e32 v63, v111
	s_branch .LBB0_1033

.LBB0_1033:
	s_cmpk_gt_u32 s3, 0x3bf
	s_cselect_b64 s[36:37], -1, 0
	s_and_b64 vcc, exec, s[36:37]
	s_waitcnt lgkmcnt(0)
	s_barrier
	s_cbranch_vccnz .Lp4_lastk_3
	v_lshl_add_u64 v[242:243], v[194:195], 0, s[8:9]
	s_waitcnt vmcnt(9)
	ds_write_b128 v189, v[70:73]
	s_nop 0
	v_add_co_u32_e32 v70, vcc, 0x200000, v242
	s_nop 1
	v_addc_co_u32_e32 v71, vcc, 0, v243, vcc
	global_load_dwordx4 v[70:73], v[70:71], off
	s_waitcnt vmcnt(9)
	ds_write_b128 v189, v[74:77] offset:4608
	s_nop 0
	v_add_co_u32_e32 v74, vcc, 0x210000, v242
	s_nop 1
	v_addc_co_u32_e32 v75, vcc, 0, v243, vcc
	global_load_dwordx4 v[74:77], v[74:75], off
	s_waitcnt vmcnt(9)
	ds_write_b128 v189, v[98:101] offset:9216
	s_nop 0
	global_load_dwordx4 v[98:101], v[194:195], off
	s_waitcnt vmcnt(9)
	ds_write_b128 v189, v[78:81] offset:13824
	s_nop 0
	v_add_co_u32_e32 v78, vcc, 0x10000, v194
	s_nop 1
	v_addc_co_u32_e32 v79, vcc, 0, v195, vcc
	global_load_dwordx4 v[78:81], v[78:79], off
	s_waitcnt vmcnt(9)
	ds_write_b128 v189, v[82:85] offset:18432
	s_nop 0
	v_add_co_u32_e32 v82, vcc, 0x20000, v194
	s_nop 1
	v_addc_co_u32_e32 v83, vcc, 0, v195, vcc
	global_load_dwordx4 v[82:85], v[82:83], off
	s_waitcnt vmcnt(9)
	ds_write_b128 v189, v[86:89] offset:23040
	s_nop 0
	v_add_co_u32_e32 v86, vcc, 0x30000, v194
	s_nop 1
	v_addc_co_u32_e32 v87, vcc, 0, v195, vcc
	global_load_dwordx4 v[86:89], v[86:87], off
	s_waitcnt vmcnt(9)
	ds_write_b128 v189, v[90:93] offset:27648
	s_nop 0
	v_add_co_u32_e32 v90, vcc, s33, v194
	s_nop 1
	v_addc_co_u32_e32 v91, vcc, 0, v195, vcc
	global_load_dwordx4 v[90:93], v[90:91], off
	s_waitcnt vmcnt(9)
	ds_write_b128 v189, v[94:97] offset:32256
	s_nop 0
	v_add_co_u32_e32 v94, vcc, 0x50000, v194
	s_nop 1
	v_addc_co_u32_e32 v95, vcc, 0, v195, vcc
	global_load_dwordx4 v[94:97], v[94:95], off
	s_waitcnt vmcnt(9)
	ds_write_b128 v189, v[102:105] offset:36864
	s_nop 0
	v_add_co_u32_e32 v102, vcc, 0x60000, v194
	s_nop 1
	v_addc_co_u32_e32 v103, vcc, 0, v195, vcc
	global_load_dwordx4 v[102:105], v[102:103], off
	s_waitcnt vmcnt(9)
	ds_write_b128 v189, v[106:109] offset:41472
	s_nop 0
	v_add_co_u32_e32 v106, vcc, 0x70000, v194
	s_nop 1
	v_addc_co_u32_e32 v107, vcc, 0, v195, vcc
	global_load_dwordx4 v[106:109], v[106:107], off
	s_waitcnt lgkmcnt(0)
	s_barrier
	s_branch .LBB0_1032
.Lp4_lastk_3:
	s_waitcnt vmcnt(0)
	ds_write_b128 v189, v[70:73]
	ds_write_b128 v189, v[74:77] offset:4608
	ds_write_b128 v189, v[98:101] offset:9216
	ds_write_b128 v189, v[78:81] offset:13824
	ds_write_b128 v189, v[82:85] offset:18432
	ds_write_b128 v189, v[86:89] offset:23040
	ds_write_b128 v189, v[90:93] offset:27648
	ds_write_b128 v189, v[94:97] offset:32256
	ds_write_b128 v189, v[102:105] offset:36864
	ds_write_b128 v189, v[106:109] offset:41472
	s_waitcnt lgkmcnt(0)
	s_barrier
	s_branch .LBB0_1032
.LBB0_1035:
	s_lshl_b64 s[0:1], s[0:1], 2
	s_add_u32 s0, s46, s0
	s_addc_u32 s1, s47, s1
	s_lshr_b32 s3, s2, 7
	s_mul_i32 s36, s3, 0xc00
	s_ashr_i32 s37, s36, 31
	s_lshl_b64 s[36:37], s[36:37], 2
	s_add_u32 s3, s4, s36
	s_addc_u32 s34, s5, s37
	s_waitcnt vmcnt(0)
	v_lshrrev_b32_e32 v70, 3, v213
	v_and_b32_e32 v202, 31, v213
	s_lshl_b32 s38, s2, 6
	v_and_b32_e32 v71, 0xffffffc0, v213
	v_and_or_b32 v194, v70, 4, v71
	v_or_b32_e32 v72, s38, v202
	s_add_u32 s36, s3, 0x2100
	v_ashrrev_i32_e32 v195, 31, v194
	v_ashrrev_i32_e32 v73, 31, v72
	s_addc_u32 s37, s34, 0
	v_lshlrev_b64 v[108:109], 2, v[194:195]
	v_lshlrev_b64 v[72:73], 12, v[72:73]
	v_lshl_add_u64 v[70:71], s[36:37], 0, v[108:109]
	v_lshl_add_u64 v[76:77], v[68:69], 0, v[72:73]
	flat_load_dwordx4 v[214:217], v[70:71]
	flat_load_dwordx4 v[218:221], v[70:71] offset:32
	flat_load_dwordx4 v[222:225], v[70:71] offset:64
	flat_load_dwordx4 v[226:229], v[70:71] offset:96
	flat_load_dwordx4 v[230:233], v[70:71] offset:128
	flat_load_dwordx4 v[234:237], v[70:71] offset:160
	flat_load_dwordx4 v[238:241], v[70:71] offset:192
	flat_load_dwordx4 v[242:245], v[70:71] offset:224
	v_lshl_add_u64 v[196:197], v[76:77], 0, v[108:109]
	flat_load_dwordx4 v[76:79], v[196:197]
	v_lshlrev_b32_e32 v110, 12, v202
	v_lshl_add_u64 v[200:201], s[0:1], 0, v[108:109]
	v_lshl_add_u64 v[198:199], v[200:201], 0, v[110:111]
	flat_load_dwordx4 v[80:83], v[196:197] offset:32
	flat_load_dwordx4 v[84:87], v[196:197] offset:64
	flat_load_dwordx4 v[88:91], v[196:197] offset:96
	flat_load_dwordx4 v[92:95], v[196:197] offset:128
	flat_load_dwordx4 v[96:99], v[196:197] offset:160
	flat_load_dwordx4 v[100:103], v[196:197] offset:192
	flat_load_dwordx4 v[104:107], v[196:197] offset:224
	v_or_b32_e32 v195, 32, v202
	v_lshlrev_b32_e32 v110, 12, v195
	s_mov_b32 s3, 0
	s_waitcnt vmcnt(0) lgkmcnt(0)
	v_mov_b64_e32 v[72:73], v[214:215]
	v_mov_b64_e32 v[74:75], v[216:217]
	v_pk_mul_f32 v[48:49], v[48:49], v[72:73]
	v_pk_mul_f32 v[50:51], v[50:51], v[74:75]
	v_pk_fma_f32 v[48:49], v[76:77], s[26:27], v[48:49] op_sel_hi:[1,0,1]
	v_pk_fma_f32 v[50:51], v[78:79], s[26:27], v[50:51] op_sel_hi:[1,0,1]
	flat_store_dwordx4 v[198:199], v[48:51]
	s_nop 1
	v_mov_b64_e32 v[48:49], v[218:219]
	v_mov_b64_e32 v[50:51], v[220:221]
	v_lshl_add_u64 v[76:77], v[200:201], 0, v[110:111]
	v_lshlrev_b32_e32 v110, 10, v202
	v_lshlrev_b32_e32 v200, 10, v195
	v_mov_b64_e32 v[202:203], v[178:179]
	v_pk_mul_f32 v[48:49], v[52:53], v[48:49]
	v_pk_mul_f32 v[50:51], v[54:55], v[50:51]
	v_pk_fma_f32 v[48:49], v[80:81], s[26:27], v[48:49] op_sel_hi:[1,0,1]
	v_pk_fma_f32 v[50:51], v[82:83], s[26:27], v[50:51] op_sel_hi:[1,0,1]
	flat_store_dwordx4 v[198:199], v[48:51] offset:32
	s_nop 1
	v_mov_b64_e32 v[48:49], v[222:223]
	v_mov_b64_e32 v[50:51], v[224:225]
	v_pk_mul_f32 v[48:49], v[56:57], v[48:49]
	v_pk_mul_f32 v[50:51], v[58:59], v[50:51]
	v_pk_fma_f32 v[48:49], v[84:85], s[26:27], v[48:49] op_sel_hi:[1,0,1]
	v_pk_fma_f32 v[50:51], v[86:87], s[26:27], v[50:51] op_sel_hi:[1,0,1]
	flat_store_dwordx4 v[198:199], v[48:51] offset:64
	s_nop 1
	v_mov_b64_e32 v[48:49], v[226:227]
	v_mov_b64_e32 v[50:51], v[228:229]
	v_pk_mul_f32 v[48:49], v[60:61], v[48:49]
	v_pk_mul_f32 v[50:51], v[62:63], v[50:51]
	v_pk_fma_f32 v[48:49], v[88:89], s[26:27], v[48:49] op_sel_hi:[1,0,1]
	v_pk_fma_f32 v[50:51], v[90:91], s[26:27], v[50:51] op_sel_hi:[1,0,1]
	flat_store_dwordx4 v[198:199], v[48:51] offset:96
	s_nop 1
	v_mov_b64_e32 v[48:49], v[230:231]
	v_mov_b64_e32 v[50:51], v[232:233]
	v_pk_mul_f32 v[32:33], v[32:33], v[48:49]
	v_pk_mul_f32 v[34:35], v[34:35], v[50:51]
	v_pk_fma_f32 v[32:33], v[92:93], s[26:27], v[32:33] op_sel_hi:[1,0,1]
	v_pk_fma_f32 v[34:35], v[94:95], s[26:27], v[34:35] op_sel_hi:[1,0,1]
	flat_store_dwordx4 v[198:199], v[32:35] offset:128
	s_nop 1
	v_mov_b64_e32 v[32:33], v[234:235]
	v_mov_b64_e32 v[34:35], v[236:237]
	v_pk_mul_f32 v[32:33], v[36:37], v[32:33]
	v_pk_mul_f32 v[34:35], v[38:39], v[34:35]
	v_pk_fma_f32 v[32:33], v[96:97], s[26:27], v[32:33] op_sel_hi:[1,0,1]
	v_pk_fma_f32 v[34:35], v[98:99], s[26:27], v[34:35] op_sel_hi:[1,0,1]
	flat_store_dwordx4 v[198:199], v[32:35] offset:160
	s_nop 1
	v_mov_b64_e32 v[32:33], v[238:239]
	v_mov_b64_e32 v[34:35], v[240:241]
	v_or_b32_e32 v36, s38, v195
	v_ashrrev_i32_e32 v37, 31, v36
	v_lshlrev_b64 v[36:37], 12, v[36:37]
	v_lshl_add_u64 v[36:37], v[68:69], 0, v[36:37]
	v_pk_mul_f32 v[32:33], v[40:41], v[32:33]
	v_pk_mul_f32 v[34:35], v[42:43], v[34:35]
	v_pk_fma_f32 v[32:33], v[100:101], s[26:27], v[32:33] op_sel_hi:[1,0,1]
	v_pk_fma_f32 v[34:35], v[102:103], s[26:27], v[34:35] op_sel_hi:[1,0,1]
	flat_store_dwordx4 v[198:199], v[32:35] offset:192
	s_nop 1
	v_mov_b64_e32 v[32:33], v[242:243]
	v_mov_b64_e32 v[34:35], v[244:245]
	v_pk_mul_f32 v[32:33], v[44:45], v[32:33]
	v_pk_mul_f32 v[34:35], v[46:47], v[34:35]
	v_pk_fma_f32 v[32:33], v[104:105], s[26:27], v[32:33] op_sel_hi:[1,0,1]
	v_pk_fma_f32 v[34:35], v[106:107], s[26:27], v[34:35] op_sel_hi:[1,0,1]
	flat_store_dwordx4 v[198:199], v[32:35] offset:224
	s_nop 1
	v_mov_b64_e32 v[32:33], v[214:215]
	v_mov_b64_e32 v[34:35], v[216:217]
	v_lshl_add_u64 v[198:199], v[36:37], 0, v[108:109]
	flat_load_dwordx4 v[36:39], v[198:199]
	flat_load_dwordx4 v[40:43], v[198:199] offset:32
	flat_load_dwordx4 v[44:47], v[198:199] offset:64
	flat_load_dwordx4 v[48:51], v[198:199] offset:96
	flat_load_dwordx4 v[52:55], v[198:199] offset:128
	flat_load_dwordx4 v[56:59], v[198:199] offset:160
	flat_load_dwordx4 v[60:63], v[198:199] offset:192
	flat_load_dwordx4 v[72:75], v[198:199] offset:224
	s_waitcnt vmcnt(0) lgkmcnt(0)
	v_pk_mul_f32 v[16:17], v[16:17], v[32:33]
	v_pk_mul_f32 v[18:19], v[18:19], v[34:35]
	v_pk_fma_f32 v[16:17], v[36:37], s[26:27], v[16:17] op_sel_hi:[1,0,1]
	v_pk_fma_f32 v[18:19], v[38:39], s[26:27], v[18:19] op_sel_hi:[1,0,1]
	flat_store_dwordx4 v[76:77], v[16:19]
	s_nop 1
	v_mov_b64_e32 v[16:17], v[218:219]
	v_mov_b64_e32 v[18:19], v[220:221]
	v_pk_mul_f32 v[16:17], v[20:21], v[16:17]
	v_pk_mul_f32 v[18:19], v[22:23], v[18:19]
	v_pk_fma_f32 v[16:17], v[40:41], s[26:27], v[16:17] op_sel_hi:[1,0,1]
	v_pk_fma_f32 v[18:19], v[42:43], s[26:27], v[18:19] op_sel_hi:[1,0,1]
	flat_store_dwordx4 v[76:77], v[16:19] offset:32
	s_nop 1
	v_mov_b64_e32 v[16:17], v[222:223]
	v_mov_b64_e32 v[18:19], v[224:225]
	v_pk_mul_f32 v[16:17], v[24:25], v[16:17]
	v_pk_mul_f32 v[18:19], v[26:27], v[18:19]
	v_pk_fma_f32 v[16:17], v[44:45], s[26:27], v[16:17] op_sel_hi:[1,0,1]
	v_pk_fma_f32 v[18:19], v[46:47], s[26:27], v[18:19] op_sel_hi:[1,0,1]
	flat_store_dwordx4 v[76:77], v[16:19] offset:64
	s_nop 1
	v_mov_b64_e32 v[16:17], v[226:227]
	v_mov_b64_e32 v[18:19], v[228:229]
	v_pk_mul_f32 v[16:17], v[28:29], v[16:17]
	v_pk_mul_f32 v[18:19], v[30:31], v[18:19]
	v_pk_fma_f32 v[16:17], v[48:49], s[26:27], v[16:17] op_sel_hi:[1,0,1]
	v_pk_fma_f32 v[18:19], v[50:51], s[26:27], v[18:19] op_sel_hi:[1,0,1]
	flat_store_dwordx4 v[76:77], v[16:19] offset:96
	s_nop 1
	v_mov_b64_e32 v[16:17], v[230:231]
	v_mov_b64_e32 v[18:19], v[232:233]
	v_pk_mul_f32 v[0:1], v[0:1], v[16:17]
	v_pk_mul_f32 v[2:3], v[2:3], v[18:19]
	v_pk_fma_f32 v[0:1], v[52:53], s[26:27], v[0:1] op_sel_hi:[1,0,1]
	v_pk_fma_f32 v[2:3], v[54:55], s[26:27], v[2:3] op_sel_hi:[1,0,1]
	flat_store_dwordx4 v[76:77], v[0:3] offset:128
	s_nop 1
	v_mov_b64_e32 v[0:1], v[234:235]
	v_mov_b64_e32 v[2:3], v[236:237]
	v_pk_mul_f32 v[0:1], v[4:5], v[0:1]
	v_pk_mul_f32 v[2:3], v[6:7], v[2:3]
	v_pk_fma_f32 v[0:1], v[56:57], s[26:27], v[0:1] op_sel_hi:[1,0,1]
	v_pk_fma_f32 v[2:3], v[58:59], s[26:27], v[2:3] op_sel_hi:[1,0,1]
	flat_store_dwordx4 v[76:77], v[0:3] offset:160
	s_nop 1
	v_mov_b64_e32 v[0:1], v[238:239]
	v_mov_b64_e32 v[2:3], v[240:241]
	v_pk_mul_f32 v[0:1], v[8:9], v[0:1]
	v_pk_mul_f32 v[2:3], v[10:11], v[2:3]
	v_pk_fma_f32 v[0:1], v[60:61], s[26:27], v[0:1] op_sel_hi:[1,0,1]
	v_pk_fma_f32 v[2:3], v[62:63], s[26:27], v[2:3] op_sel_hi:[1,0,1]
	flat_store_dwordx4 v[76:77], v[0:3] offset:192
	s_nop 1
	v_mov_b64_e32 v[0:1], v[242:243]
	v_mov_b64_e32 v[2:3], v[244:245]
	v_pk_mul_f32 v[0:1], v[12:13], v[0:1]
	v_pk_mul_f32 v[2:3], v[14:15], v[2:3]
	v_pk_fma_f32 v[0:1], v[72:73], s[26:27], v[0:1] op_sel_hi:[1,0,1]
	v_pk_fma_f32 v[2:3], v[74:75], s[26:27], v[2:3] op_sel_hi:[1,0,1]
	flat_store_dwordx4 v[76:77], v[0:3] offset:224
	global_load_dwordx4 v[70:73], v[190:191], off
	s_nop 0
	global_load_dwordx4 v[74:77], v[192:193], off
	global_load_dwordx4 v[98:101], v[128:129], off
	global_load_dwordx4 v[78:81], v[130:131], off
	global_load_dwordx4 v[82:85], v[132:133], off
	global_load_dwordx4 v[86:89], v[134:135], off
	global_load_dwordx4 v[90:93], v[136:137], off
	global_load_dwordx4 v[94:97], v[138:139], off
	global_load_dwordx4 v[102:105], v[140:141], off
	global_load_dwordx4 v[106:109], v[142:143], off
	v_mov_b32_e32 v0, 0
	v_mov_b32_e32 v1, v0
	v_mov_b32_e32 v2, v0
	v_mov_b32_e32 v3, v0
	v_mov_b32_e32 v4, v0
	v_mov_b32_e32 v5, v0
	v_mov_b32_e32 v6, v0
	v_mov_b32_e32 v7, v0
	v_mov_b32_e32 v8, v0
	v_mov_b32_e32 v9, v0
	v_mov_b32_e32 v10, v0
	v_mov_b32_e32 v11, v0
	v_mov_b32_e32 v12, v0
	v_mov_b32_e32 v13, v0
	v_mov_b32_e32 v14, v0
	v_mov_b32_e32 v15, v0
	v_mov_b32_e32 v16, v0
	v_mov_b32_e32 v17, v0
	v_mov_b32_e32 v18, v0
	v_mov_b32_e32 v19, v0
	v_mov_b32_e32 v20, v0
	v_mov_b32_e32 v21, v0
	v_mov_b32_e32 v22, v0
	v_mov_b32_e32 v23, v0
	v_mov_b32_e32 v24, v0
	v_mov_b32_e32 v25, v0
	v_mov_b32_e32 v26, v0
	v_mov_b32_e32 v27, v0
	v_mov_b32_e32 v28, v0
	v_mov_b32_e32 v29, v0
	v_mov_b32_e32 v30, v0
	v_mov_b32_e32 v31, v0
	v_mov_b32_e32 v32, v0
	v_mov_b32_e32 v33, v0
	v_mov_b32_e32 v34, v0
	v_mov_b32_e32 v35, v0
	v_mov_b32_e32 v36, v0
	v_mov_b32_e32 v37, v0
	v_mov_b32_e32 v38, v0
	v_mov_b32_e32 v39, v0
	v_mov_b32_e32 v40, v0
	v_mov_b32_e32 v41, v0
	v_mov_b32_e32 v42, v0
	v_mov_b32_e32 v43, v0
	v_mov_b32_e32 v44, v0
	v_mov_b32_e32 v45, v0
	v_mov_b32_e32 v46, v0
	v_mov_b32_e32 v47, v0
	v_mov_b32_e32 v48, v0
	v_mov_b32_e32 v49, v0
	v_mov_b32_e32 v50, v0
	v_mov_b32_e32 v51, v0
	v_mov_b32_e32 v52, v0
	v_mov_b32_e32 v53, v0
	v_mov_b32_e32 v54, v0
	v_mov_b32_e32 v55, v0
	v_mov_b32_e32 v56, v0
	v_mov_b32_e32 v57, v0
	v_mov_b32_e32 v58, v0
	v_mov_b32_e32 v59, v0
	v_mov_b32_e32 v60, v0
	v_mov_b32_e32 v61, v0
	v_mov_b32_e32 v62, v0
	v_mov_b32_e32 v63, v0
	s_branch .LBB0_1037

.LBB0_1037:
	s_cmpk_gt_u32 s3, 0x3bf
	s_cselect_b64 s[38:39], -1, 0
	s_and_b64 vcc, exec, s[38:39]
	s_waitcnt lgkmcnt(0)
	s_barrier
	s_cbranch_vccnz .Lp4_lastk_2
	v_lshl_add_u64 v[242:243], v[202:203], 0, s[8:9]
	s_waitcnt vmcnt(9)
	ds_write_b128 v189, v[70:73]
	s_nop 0
	v_add_co_u32_e32 v70, vcc, 0x180000, v242
	s_nop 1
	v_addc_co_u32_e32 v71, vcc, 0, v243, vcc
	global_load_dwordx4 v[70:73], v[70:71], off
	s_waitcnt vmcnt(9)
	ds_write_b128 v189, v[74:77] offset:4608
	s_nop 0
	v_add_co_u32_e32 v74, vcc, 0x190000, v242
	s_nop 1
	v_addc_co_u32_e32 v75, vcc, 0, v243, vcc
	global_load_dwordx4 v[74:77], v[74:75], off
	s_waitcnt vmcnt(9)
	ds_write_b128 v189, v[98:101] offset:9216
	s_nop 0
	global_load_dwordx4 v[98:101], v[202:203], off
	s_waitcnt vmcnt(9)
	ds_write_b128 v189, v[78:81] offset:13824
	s_nop 0
	v_add_co_u32_e32 v78, vcc, 0x10000, v202
	s_nop 1
	v_addc_co_u32_e32 v79, vcc, 0, v203, vcc
	global_load_dwordx4 v[78:81], v[78:79], off
	s_waitcnt vmcnt(9)
	ds_write_b128 v189, v[82:85] offset:18432
	s_nop 0
	v_add_co_u32_e32 v82, vcc, 0x20000, v202
	s_nop 1
	v_addc_co_u32_e32 v83, vcc, 0, v203, vcc
	global_load_dwordx4 v[82:85], v[82:83], off
	s_waitcnt vmcnt(9)
	ds_write_b128 v189, v[86:89] offset:23040
	s_nop 0
	v_add_co_u32_e32 v86, vcc, 0x30000, v202
	s_nop 1
	v_addc_co_u32_e32 v87, vcc, 0, v203, vcc
	global_load_dwordx4 v[86:89], v[86:87], off
	s_waitcnt vmcnt(9)
	ds_write_b128 v189, v[90:93] offset:27648
	s_nop 0
	v_add_co_u32_e32 v90, vcc, s33, v202
	s_nop 1
	v_addc_co_u32_e32 v91, vcc, 0, v203, vcc
	global_load_dwordx4 v[90:93], v[90:91], off
	s_waitcnt vmcnt(9)
	ds_write_b128 v189, v[94:97] offset:32256
	s_nop 0
	v_add_co_u32_e32 v94, vcc, 0x50000, v202
	s_nop 1
	v_addc_co_u32_e32 v95, vcc, 0, v203, vcc
	global_load_dwordx4 v[94:97], v[94:95], off
	s_waitcnt vmcnt(9)
	ds_write_b128 v189, v[102:105] offset:36864
	s_nop 0
	v_add_co_u32_e32 v102, vcc, 0x60000, v202
	s_nop 1
	v_addc_co_u32_e32 v103, vcc, 0, v203, vcc
	global_load_dwordx4 v[102:105], v[102:103], off
	s_waitcnt vmcnt(9)
	ds_write_b128 v189, v[106:109] offset:41472
	s_nop 0
	v_add_co_u32_e32 v106, vcc, 0x70000, v202
	s_nop 1
	v_addc_co_u32_e32 v107, vcc, 0, v203, vcc
	global_load_dwordx4 v[106:109], v[106:107], off
	s_waitcnt lgkmcnt(0)
	s_barrier
	s_branch .LBB0_1036

.LBB0_1039:
	s_waitcnt vmcnt(0)
	v_add_u32_e32 v70, 0x100, v194
	v_ashrrev_i32_e32 v71, 31, v70
	v_lshlrev_b64 v[108:109], 2, v[70:71]
	v_lshl_add_u64 v[70:71], s[36:37], 0, v[108:109]
	flat_load_dwordx4 v[214:217], v[70:71]
	flat_load_dwordx4 v[218:221], v[70:71] offset:32
	flat_load_dwordx4 v[222:225], v[70:71] offset:64
	flat_load_dwordx4 v[226:229], v[70:71] offset:96
	flat_load_dwordx4 v[230:233], v[70:71] offset:128
	flat_load_dwordx4 v[234:237], v[70:71] offset:160
	flat_load_dwordx4 v[238:241], v[70:71] offset:192
	flat_load_dwordx4 v[242:245], v[70:71] offset:224
	flat_load_dwordx4 v[76:79], v[196:197] offset:1024
	flat_load_dwordx4 v[80:83], v[196:197] offset:1056
	flat_load_dwordx4 v[84:87], v[196:197] offset:1088
	flat_load_dwordx4 v[88:91], v[196:197] offset:1120
	flat_load_dwordx4 v[92:95], v[196:197] offset:1152
	flat_load_dwordx4 v[96:99], v[196:197] offset:1184
	flat_load_dwordx4 v[100:103], v[196:197] offset:1216
	flat_load_dwordx4 v[104:107], v[196:197] offset:1248
	v_lshlrev_b32_e32 v110, 2, v110
	v_lshl_add_u64 v[108:109], s[0:1], 0, v[108:109]
	v_lshl_add_u64 v[202:203], v[108:109], 0, v[110:111]
	v_lshlrev_b32_e32 v200, 2, v200
	v_mov_b32_e32 v201, v111
	s_mov_b32 s3, 0
	s_waitcnt vmcnt(0) lgkmcnt(0)
	v_mov_b64_e32 v[72:73], v[214:215]
	v_mov_b64_e32 v[74:75], v[216:217]
	v_pk_mul_f32 v[48:49], v[48:49], v[72:73]
	v_pk_mul_f32 v[50:51], v[50:51], v[74:75]
	v_pk_fma_f32 v[48:49], v[76:77], s[26:27], v[48:49] op_sel_hi:[1,0,1]
	v_pk_fma_f32 v[50:51], v[78:79], s[26:27], v[50:51] op_sel_hi:[1,0,1]
	flat_store_dwordx4 v[202:203], v[48:51]
	s_nop 1
	v_mov_b64_e32 v[48:49], v[218:219]
	v_mov_b64_e32 v[50:51], v[220:221]
	v_lshl_add_u64 v[76:77], v[108:109], 0, v[200:201]
	v_pk_mul_f32 v[48:49], v[52:53], v[48:49]
	v_pk_mul_f32 v[50:51], v[54:55], v[50:51]
	v_pk_fma_f32 v[48:49], v[80:81], s[26:27], v[48:49] op_sel_hi:[1,0,1]
	v_pk_fma_f32 v[50:51], v[82:83], s[26:27], v[50:51] op_sel_hi:[1,0,1]
	flat_store_dwordx4 v[202:203], v[48:51] offset:32
	s_nop 1
	v_mov_b64_e32 v[48:49], v[222:223]
	v_mov_b64_e32 v[50:51], v[224:225]
	v_pk_mul_f32 v[48:49], v[56:57], v[48:49]
	v_pk_mul_f32 v[50:51], v[58:59], v[50:51]
	v_pk_fma_f32 v[48:49], v[84:85], s[26:27], v[48:49] op_sel_hi:[1,0,1]
	v_pk_fma_f32 v[50:51], v[86:87], s[26:27], v[50:51] op_sel_hi:[1,0,1]
	flat_store_dwordx4 v[202:203], v[48:51] offset:64
	s_nop 1
	v_mov_b64_e32 v[48:49], v[226:227]
	v_mov_b64_e32 v[50:51], v[228:229]
	v_pk_mul_f32 v[48:49], v[60:61], v[48:49]
	v_pk_mul_f32 v[50:51], v[62:63], v[50:51]
	v_pk_fma_f32 v[48:49], v[88:89], s[26:27], v[48:49] op_sel_hi:[1,0,1]
	v_pk_fma_f32 v[50:51], v[90:91], s[26:27], v[50:51] op_sel_hi:[1,0,1]
	flat_store_dwordx4 v[202:203], v[48:51] offset:96
	s_nop 1
	v_mov_b64_e32 v[48:49], v[230:231]
	v_mov_b64_e32 v[50:51], v[232:233]
	v_pk_mul_f32 v[32:33], v[32:33], v[48:49]
	v_pk_mul_f32 v[34:35], v[34:35], v[50:51]
	v_pk_fma_f32 v[32:33], v[92:93], s[26:27], v[32:33] op_sel_hi:[1,0,1]
	v_pk_fma_f32 v[34:35], v[94:95], s[26:27], v[34:35] op_sel_hi:[1,0,1]
	flat_store_dwordx4 v[202:203], v[32:35] offset:128
	s_nop 1
	v_mov_b64_e32 v[32:33], v[234:235]
	v_mov_b64_e32 v[34:35], v[236:237]
	v_pk_mul_f32 v[32:33], v[36:37], v[32:33]
	v_pk_mul_f32 v[34:35], v[38:39], v[34:35]
	v_pk_fma_f32 v[32:33], v[96:97], s[26:27], v[32:33] op_sel_hi:[1,0,1]
	v_pk_fma_f32 v[34:35], v[98:99], s[26:27], v[34:35] op_sel_hi:[1,0,1]
	flat_store_dwordx4 v[202:203], v[32:35] offset:160
	s_nop 1
	v_mov_b64_e32 v[32:33], v[238:239]
	v_mov_b64_e32 v[34:35], v[240:241]
	v_pk_mul_f32 v[32:33], v[40:41], v[32:33]
	v_pk_mul_f32 v[34:35], v[42:43], v[34:35]
	v_pk_fma_f32 v[32:33], v[100:101], s[26:27], v[32:33] op_sel_hi:[1,0,1]
	v_pk_fma_f32 v[34:35], v[102:103], s[26:27], v[34:35] op_sel_hi:[1,0,1]
	flat_store_dwordx4 v[202:203], v[32:35] offset:192
	s_nop 1
	v_mov_b64_e32 v[32:33], v[242:243]
	v_mov_b64_e32 v[34:35], v[244:245]
	v_pk_mul_f32 v[32:33], v[44:45], v[32:33]
	v_pk_mul_f32 v[34:35], v[46:47], v[34:35]
	v_pk_fma_f32 v[32:33], v[104:105], s[26:27], v[32:33] op_sel_hi:[1,0,1]
	v_pk_fma_f32 v[34:35], v[106:107], s[26:27], v[34:35] op_sel_hi:[1,0,1]
	flat_store_dwordx4 v[202:203], v[32:35] offset:224
	s_nop 1
	v_mov_b64_e32 v[32:33], v[214:215]
	v_mov_b64_e32 v[34:35], v[216:217]
	s_nop 0
	flat_load_dwordx4 v[36:39], v[198:199] offset:1024
	flat_load_dwordx4 v[40:43], v[198:199] offset:1056
	flat_load_dwordx4 v[44:47], v[198:199] offset:1088
	flat_load_dwordx4 v[48:51], v[198:199] offset:1120
	flat_load_dwordx4 v[52:55], v[198:199] offset:1152
	flat_load_dwordx4 v[56:59], v[198:199] offset:1184
	flat_load_dwordx4 v[60:63], v[198:199] offset:1216
	flat_load_dwordx4 v[72:75], v[198:199] offset:1248
	v_mov_b64_e32 v[202:203], v[180:181]
	s_waitcnt vmcnt(0) lgkmcnt(0)
	v_pk_mul_f32 v[16:17], v[16:17], v[32:33]
	v_pk_mul_f32 v[18:19], v[18:19], v[34:35]
	v_pk_fma_f32 v[16:17], v[36:37], s[26:27], v[16:17] op_sel_hi:[1,0,1]
	v_pk_fma_f32 v[18:19], v[38:39], s[26:27], v[18:19] op_sel_hi:[1,0,1]
	flat_store_dwordx4 v[76:77], v[16:19]
	s_nop 1
	v_mov_b64_e32 v[16:17], v[218:219]
	v_mov_b64_e32 v[18:19], v[220:221]
	v_pk_mul_f32 v[16:17], v[20:21], v[16:17]
	v_pk_mul_f32 v[18:19], v[22:23], v[18:19]
	v_pk_fma_f32 v[16:17], v[40:41], s[26:27], v[16:17] op_sel_hi:[1,0,1]
	v_pk_fma_f32 v[18:19], v[42:43], s[26:27], v[18:19] op_sel_hi:[1,0,1]
	flat_store_dwordx4 v[76:77], v[16:19] offset:32
	s_nop 1
	v_mov_b64_e32 v[16:17], v[222:223]
	v_mov_b64_e32 v[18:19], v[224:225]
	v_pk_mul_f32 v[16:17], v[24:25], v[16:17]
	v_pk_mul_f32 v[18:19], v[26:27], v[18:19]
	v_pk_fma_f32 v[16:17], v[44:45], s[26:27], v[16:17] op_sel_hi:[1,0,1]
	v_pk_fma_f32 v[18:19], v[46:47], s[26:27], v[18:19] op_sel_hi:[1,0,1]
	flat_store_dwordx4 v[76:77], v[16:19] offset:64
	s_nop 1
	v_mov_b64_e32 v[16:17], v[226:227]
	v_mov_b64_e32 v[18:19], v[228:229]
	v_pk_mul_f32 v[16:17], v[28:29], v[16:17]
	v_pk_mul_f32 v[18:19], v[30:31], v[18:19]
	v_pk_fma_f32 v[16:17], v[48:49], s[26:27], v[16:17] op_sel_hi:[1,0,1]
	v_pk_fma_f32 v[18:19], v[50:51], s[26:27], v[18:19] op_sel_hi:[1,0,1]
	flat_store_dwordx4 v[76:77], v[16:19] offset:96
	s_nop 1
	v_mov_b64_e32 v[16:17], v[230:231]
	v_mov_b64_e32 v[18:19], v[232:233]
	v_pk_mul_f32 v[0:1], v[0:1], v[16:17]
	v_pk_mul_f32 v[2:3], v[2:3], v[18:19]
	v_pk_fma_f32 v[0:1], v[52:53], s[26:27], v[0:1] op_sel_hi:[1,0,1]
	v_pk_fma_f32 v[2:3], v[54:55], s[26:27], v[2:3] op_sel_hi:[1,0,1]
	flat_store_dwordx4 v[76:77], v[0:3] offset:128
	s_nop 1
	v_mov_b64_e32 v[0:1], v[234:235]
	v_mov_b64_e32 v[2:3], v[236:237]
	v_pk_mul_f32 v[0:1], v[4:5], v[0:1]
	v_pk_mul_f32 v[2:3], v[6:7], v[2:3]
	v_pk_fma_f32 v[0:1], v[56:57], s[26:27], v[0:1] op_sel_hi:[1,0,1]
	v_pk_fma_f32 v[2:3], v[58:59], s[26:27], v[2:3] op_sel_hi:[1,0,1]
	flat_store_dwordx4 v[76:77], v[0:3] offset:160
	s_nop 1
	v_mov_b64_e32 v[0:1], v[238:239]
	v_mov_b64_e32 v[2:3], v[240:241]
	v_pk_mul_f32 v[0:1], v[8:9], v[0:1]
	v_pk_mul_f32 v[2:3], v[10:11], v[2:3]
	v_pk_fma_f32 v[0:1], v[60:61], s[26:27], v[0:1] op_sel_hi:[1,0,1]
	v_pk_fma_f32 v[2:3], v[62:63], s[26:27], v[2:3] op_sel_hi:[1,0,1]
	flat_store_dwordx4 v[76:77], v[0:3] offset:192
	s_nop 1
	v_mov_b64_e32 v[0:1], v[242:243]
	v_mov_b64_e32 v[2:3], v[244:245]
	v_pk_mul_f32 v[0:1], v[12:13], v[0:1]
	v_pk_mul_f32 v[2:3], v[14:15], v[2:3]
	v_pk_fma_f32 v[0:1], v[72:73], s[26:27], v[0:1] op_sel_hi:[1,0,1]
	v_pk_fma_f32 v[2:3], v[74:75], s[26:27], v[2:3] op_sel_hi:[1,0,1]
	flat_store_dwordx4 v[76:77], v[0:3] offset:224
	global_load_dwordx4 v[70:73], v[190:191], off
	s_nop 0
	global_load_dwordx4 v[74:77], v[192:193], off
	global_load_dwordx4 v[98:101], v[144:145], off
	global_load_dwordx4 v[78:81], v[146:147], off
	global_load_dwordx4 v[82:85], v[148:149], off
	global_load_dwordx4 v[86:89], v[150:151], off
	global_load_dwordx4 v[90:93], v[152:153], off
	global_load_dwordx4 v[94:97], v[154:155], off
	global_load_dwordx4 v[102:105], v[156:157], off
	global_load_dwordx4 v[106:109], v[158:159], off
	v_mov_b32_e32 v0, 0
	v_mov_b32_e32 v1, v0
	v_mov_b32_e32 v2, v0
	v_mov_b32_e32 v3, v0
	v_mov_b32_e32 v4, v0
	v_mov_b32_e32 v5, v0
	v_mov_b32_e32 v6, v0
	v_mov_b32_e32 v7, v0
	v_mov_b32_e32 v8, v0
	v_mov_b32_e32 v9, v0
	v_mov_b32_e32 v10, v0
	v_mov_b32_e32 v11, v0
	v_mov_b32_e32 v12, v0
	v_mov_b32_e32 v13, v0
	v_mov_b32_e32 v14, v0
	v_mov_b32_e32 v15, v0
	v_mov_b32_e32 v16, v0
	v_mov_b32_e32 v17, v0
	v_mov_b32_e32 v18, v0
	v_mov_b32_e32 v19, v0
	v_mov_b32_e32 v20, v0
	v_mov_b32_e32 v21, v0
	v_mov_b32_e32 v22, v0
	v_mov_b32_e32 v23, v0
	v_mov_b32_e32 v24, v0
	v_mov_b32_e32 v25, v0
	v_mov_b32_e32 v26, v0
	v_mov_b32_e32 v27, v0
	v_mov_b32_e32 v28, v0
	v_mov_b32_e32 v29, v0
	v_mov_b32_e32 v30, v0
	v_mov_b32_e32 v31, v0
	v_mov_b32_e32 v32, v0
	v_mov_b32_e32 v33, v0
	v_mov_b32_e32 v34, v0
	v_mov_b32_e32 v35, v0
	v_mov_b32_e32 v36, v0
	v_mov_b32_e32 v37, v0
	v_mov_b32_e32 v38, v0
	v_mov_b32_e32 v39, v0
	v_mov_b32_e32 v40, v0
	v_mov_b32_e32 v41, v0
	v_mov_b32_e32 v42, v0
	v_mov_b32_e32 v43, v0
	v_mov_b32_e32 v44, v0
	v_mov_b32_e32 v45, v0
	v_mov_b32_e32 v46, v0
	v_mov_b32_e32 v47, v0
	v_mov_b32_e32 v48, v0
	v_mov_b32_e32 v49, v0
	v_mov_b32_e32 v50, v0
	v_mov_b32_e32 v51, v0
	v_mov_b32_e32 v52, v0
	v_mov_b32_e32 v53, v0
	v_mov_b32_e32 v54, v0
	v_mov_b32_e32 v55, v0
	v_mov_b32_e32 v56, v0
	v_mov_b32_e32 v57, v0
	v_mov_b32_e32 v58, v0
	v_mov_b32_e32 v59, v0
	v_mov_b32_e32 v60, v0
	v_mov_b32_e32 v61, v0
	v_mov_b32_e32 v62, v0
	v_mov_b32_e32 v63, v0
	s_branch .LBB0_1041

.LBB0_1041:
	s_cmpk_gt_u32 s3, 0x3bf
	s_cselect_b64 s[38:39], -1, 0
	s_and_b64 vcc, exec, s[38:39]
	s_waitcnt lgkmcnt(0)
	s_barrier
	s_cbranch_vccnz .Lp4_lastk_1
	v_lshl_add_u64 v[242:243], v[202:203], 0, s[8:9]
	s_waitcnt vmcnt(9)
	ds_write_b128 v189, v[70:73]
	s_nop 0
	v_add_co_u32_e32 v70, vcc, 0x100000, v242
	s_nop 1
	v_addc_co_u32_e32 v71, vcc, 0, v243, vcc
	global_load_dwordx4 v[70:73], v[70:71], off
	s_waitcnt vmcnt(9)
	ds_write_b128 v189, v[74:77] offset:4608
	s_nop 0
	v_add_co_u32_e32 v74, vcc, 0x110000, v242
	s_nop 1
	v_addc_co_u32_e32 v75, vcc, 0, v243, vcc
	global_load_dwordx4 v[74:77], v[74:75], off
	s_waitcnt vmcnt(9)
	ds_write_b128 v189, v[98:101] offset:9216
	s_nop 0
	global_load_dwordx4 v[98:101], v[202:203], off
	s_waitcnt vmcnt(9)
	ds_write_b128 v189, v[78:81] offset:13824
	s_nop 0
	v_add_co_u32_e32 v78, vcc, 0x10000, v202
	s_nop 1
	v_addc_co_u32_e32 v79, vcc, 0, v203, vcc
	global_load_dwordx4 v[78:81], v[78:79], off
	s_waitcnt vmcnt(9)
	ds_write_b128 v189, v[82:85] offset:18432
	s_nop 0
	v_add_co_u32_e32 v82, vcc, 0x20000, v202
	s_nop 1
	v_addc_co_u32_e32 v83, vcc, 0, v203, vcc
	global_load_dwordx4 v[82:85], v[82:83], off
	s_waitcnt vmcnt(9)
	ds_write_b128 v189, v[86:89] offset:23040
	s_nop 0
	v_add_co_u32_e32 v86, vcc, 0x30000, v202
	s_nop 1
	v_addc_co_u32_e32 v87, vcc, 0, v203, vcc
	global_load_dwordx4 v[86:89], v[86:87], off
	s_waitcnt vmcnt(9)
	ds_write_b128 v189, v[90:93] offset:27648
	s_nop 0
	v_add_co_u32_e32 v90, vcc, s33, v202
	s_nop 1
	v_addc_co_u32_e32 v91, vcc, 0, v203, vcc
	global_load_dwordx4 v[90:93], v[90:91], off
	s_waitcnt vmcnt(9)
	ds_write_b128 v189, v[94:97] offset:32256
	s_nop 0
	v_add_co_u32_e32 v94, vcc, 0x50000, v202
	s_nop 1
	v_addc_co_u32_e32 v95, vcc, 0, v203, vcc
	global_load_dwordx4 v[94:97], v[94:95], off
	s_waitcnt vmcnt(9)
	ds_write_b128 v189, v[102:105] offset:36864
	s_nop 0
	v_add_co_u32_e32 v102, vcc, 0x60000, v202
	s_nop 1
	v_addc_co_u32_e32 v103, vcc, 0, v203, vcc
	global_load_dwordx4 v[102:105], v[102:103], off
	s_waitcnt vmcnt(9)
	ds_write_b128 v189, v[106:109] offset:41472
	s_nop 0
	v_add_co_u32_e32 v106, vcc, 0x70000, v202
	s_nop 1
	v_addc_co_u32_e32 v107, vcc, 0, v203, vcc
	global_load_dwordx4 v[106:109], v[106:107], off
	s_waitcnt lgkmcnt(0)
	s_barrier
	s_branch .LBB0_1040

.LBB0_1043:
	s_waitcnt vmcnt(0)
	v_add_u32_e32 v70, 0x200, v194
	v_ashrrev_i32_e32 v71, 31, v70
	v_lshlrev_b64 v[108:109], 2, v[70:71]
	v_lshl_add_u64 v[70:71], s[36:37], 0, v[108:109]
	flat_load_dwordx4 v[214:217], v[70:71]
	flat_load_dwordx4 v[218:221], v[70:71] offset:32
	flat_load_dwordx4 v[222:225], v[70:71] offset:64
	flat_load_dwordx4 v[226:229], v[70:71] offset:96
	flat_load_dwordx4 v[230:233], v[70:71] offset:128
	flat_load_dwordx4 v[234:237], v[70:71] offset:160
	flat_load_dwordx4 v[238:241], v[70:71] offset:192
	flat_load_dwordx4 v[242:245], v[70:71] offset:224
	flat_load_dwordx4 v[76:79], v[196:197] offset:2048
	flat_load_dwordx4 v[80:83], v[196:197] offset:2080
	flat_load_dwordx4 v[84:87], v[196:197] offset:2112
	flat_load_dwordx4 v[88:91], v[196:197] offset:2144
	flat_load_dwordx4 v[92:95], v[196:197] offset:2176
	flat_load_dwordx4 v[96:99], v[196:197] offset:2208
	flat_load_dwordx4 v[100:103], v[196:197] offset:2240
	flat_load_dwordx4 v[104:107], v[196:197] offset:2272
	v_lshl_add_u64 v[108:109], s[0:1], 0, v[108:109]
	v_lshl_add_u64 v[202:203], v[108:109], 0, v[110:111]
	v_mov_b32_e32 v201, v111
	s_mov_b32 s3, 0
	s_waitcnt vmcnt(0) lgkmcnt(0)
	v_mov_b64_e32 v[72:73], v[214:215]
	v_mov_b64_e32 v[74:75], v[216:217]
	v_pk_mul_f32 v[48:49], v[48:49], v[72:73]
	v_pk_mul_f32 v[50:51], v[50:51], v[74:75]
	v_pk_fma_f32 v[48:49], v[76:77], s[26:27], v[48:49] op_sel_hi:[1,0,1]
	v_pk_fma_f32 v[50:51], v[78:79], s[26:27], v[50:51] op_sel_hi:[1,0,1]
	flat_store_dwordx4 v[202:203], v[48:51]
	s_nop 1
	v_mov_b64_e32 v[48:49], v[218:219]
	v_mov_b64_e32 v[50:51], v[220:221]
	v_lshl_add_u64 v[76:77], v[108:109], 0, v[200:201]
	v_pk_mul_f32 v[48:49], v[52:53], v[48:49]
	v_pk_mul_f32 v[50:51], v[54:55], v[50:51]
	v_pk_fma_f32 v[48:49], v[80:81], s[26:27], v[48:49] op_sel_hi:[1,0,1]
	v_pk_fma_f32 v[50:51], v[82:83], s[26:27], v[50:51] op_sel_hi:[1,0,1]
	flat_store_dwordx4 v[202:203], v[48:51] offset:32
	s_nop 1
	v_mov_b64_e32 v[48:49], v[222:223]
	v_mov_b64_e32 v[50:51], v[224:225]
	v_pk_mul_f32 v[48:49], v[56:57], v[48:49]
	v_pk_mul_f32 v[50:51], v[58:59], v[50:51]
	v_pk_fma_f32 v[48:49], v[84:85], s[26:27], v[48:49] op_sel_hi:[1,0,1]
	v_pk_fma_f32 v[50:51], v[86:87], s[26:27], v[50:51] op_sel_hi:[1,0,1]
	flat_store_dwordx4 v[202:203], v[48:51] offset:64
	s_nop 1
	v_mov_b64_e32 v[48:49], v[226:227]
	v_mov_b64_e32 v[50:51], v[228:229]
	v_pk_mul_f32 v[48:49], v[60:61], v[48:49]
	v_pk_mul_f32 v[50:51], v[62:63], v[50:51]
	v_pk_fma_f32 v[48:49], v[88:89], s[26:27], v[48:49] op_sel_hi:[1,0,1]
	v_pk_fma_f32 v[50:51], v[90:91], s[26:27], v[50:51] op_sel_hi:[1,0,1]
	flat_store_dwordx4 v[202:203], v[48:51] offset:96
	s_nop 1
	v_mov_b64_e32 v[48:49], v[230:231]
	v_mov_b64_e32 v[50:51], v[232:233]
	v_pk_mul_f32 v[32:33], v[32:33], v[48:49]
	v_pk_mul_f32 v[34:35], v[34:35], v[50:51]
	v_pk_fma_f32 v[32:33], v[92:93], s[26:27], v[32:33] op_sel_hi:[1,0,1]
	v_pk_fma_f32 v[34:35], v[94:95], s[26:27], v[34:35] op_sel_hi:[1,0,1]
	flat_store_dwordx4 v[202:203], v[32:35] offset:128
	s_nop 1
	v_mov_b64_e32 v[32:33], v[234:235]
	v_mov_b64_e32 v[34:35], v[236:237]
	v_pk_mul_f32 v[32:33], v[36:37], v[32:33]
	v_pk_mul_f32 v[34:35], v[38:39], v[34:35]
	v_pk_fma_f32 v[32:33], v[96:97], s[26:27], v[32:33] op_sel_hi:[1,0,1]
	v_pk_fma_f32 v[34:35], v[98:99], s[26:27], v[34:35] op_sel_hi:[1,0,1]
	flat_store_dwordx4 v[202:203], v[32:35] offset:160
	s_nop 1
	v_mov_b64_e32 v[32:33], v[238:239]
	v_mov_b64_e32 v[34:35], v[240:241]
	v_pk_mul_f32 v[32:33], v[40:41], v[32:33]
	v_pk_mul_f32 v[34:35], v[42:43], v[34:35]
	v_pk_fma_f32 v[32:33], v[100:101], s[26:27], v[32:33] op_sel_hi:[1,0,1]
	v_pk_fma_f32 v[34:35], v[102:103], s[26:27], v[34:35] op_sel_hi:[1,0,1]
	flat_store_dwordx4 v[202:203], v[32:35] offset:192
	s_nop 1
	v_mov_b64_e32 v[32:33], v[242:243]
	v_mov_b64_e32 v[34:35], v[244:245]
	v_pk_mul_f32 v[32:33], v[44:45], v[32:33]
	v_pk_mul_f32 v[34:35], v[46:47], v[34:35]
	v_pk_fma_f32 v[32:33], v[104:105], s[26:27], v[32:33] op_sel_hi:[1,0,1]
	v_pk_fma_f32 v[34:35], v[106:107], s[26:27], v[34:35] op_sel_hi:[1,0,1]
	flat_store_dwordx4 v[202:203], v[32:35] offset:224
	s_nop 1
	v_mov_b64_e32 v[32:33], v[214:215]
	v_mov_b64_e32 v[34:35], v[216:217]
	s_nop 0
	flat_load_dwordx4 v[36:39], v[198:199] offset:2048
	flat_load_dwordx4 v[40:43], v[198:199] offset:2080
	flat_load_dwordx4 v[44:47], v[198:199] offset:2112
	flat_load_dwordx4 v[48:51], v[198:199] offset:2144
	flat_load_dwordx4 v[52:55], v[198:199] offset:2176
	flat_load_dwordx4 v[56:59], v[198:199] offset:2208
	flat_load_dwordx4 v[60:63], v[198:199] offset:2240
	flat_load_dwordx4 v[72:75], v[198:199] offset:2272
	s_waitcnt vmcnt(0) lgkmcnt(0)
	v_pk_mul_f32 v[16:17], v[16:17], v[32:33]
	v_pk_mul_f32 v[18:19], v[18:19], v[34:35]
	v_pk_fma_f32 v[16:17], v[36:37], s[26:27], v[16:17] op_sel_hi:[1,0,1]
	v_pk_fma_f32 v[18:19], v[38:39], s[26:27], v[18:19] op_sel_hi:[1,0,1]
	flat_store_dwordx4 v[76:77], v[16:19]
	s_nop 1
	v_mov_b64_e32 v[16:17], v[218:219]
	v_mov_b64_e32 v[18:19], v[220:221]
	v_pk_mul_f32 v[16:17], v[20:21], v[16:17]
	v_pk_mul_f32 v[18:19], v[22:23], v[18:19]
	v_pk_fma_f32 v[16:17], v[40:41], s[26:27], v[16:17] op_sel_hi:[1,0,1]
	v_pk_fma_f32 v[18:19], v[42:43], s[26:27], v[18:19] op_sel_hi:[1,0,1]
	flat_store_dwordx4 v[76:77], v[16:19] offset:32
	s_nop 1
	v_mov_b64_e32 v[16:17], v[222:223]
	v_mov_b64_e32 v[18:19], v[224:225]
	v_pk_mul_f32 v[16:17], v[24:25], v[16:17]
	v_pk_mul_f32 v[18:19], v[26:27], v[18:19]
	v_pk_fma_f32 v[16:17], v[44:45], s[26:27], v[16:17] op_sel_hi:[1,0,1]
	v_pk_fma_f32 v[18:19], v[46:47], s[26:27], v[18:19] op_sel_hi:[1,0,1]
	flat_store_dwordx4 v[76:77], v[16:19] offset:64
	s_nop 1
	v_mov_b64_e32 v[16:17], v[226:227]
	v_mov_b64_e32 v[18:19], v[228:229]
	v_pk_mul_f32 v[16:17], v[28:29], v[16:17]
	v_pk_mul_f32 v[18:19], v[30:31], v[18:19]
	v_pk_fma_f32 v[16:17], v[48:49], s[26:27], v[16:17] op_sel_hi:[1,0,1]
	v_pk_fma_f32 v[18:19], v[50:51], s[26:27], v[18:19] op_sel_hi:[1,0,1]
	flat_store_dwordx4 v[76:77], v[16:19] offset:96
	s_nop 1
	v_mov_b64_e32 v[16:17], v[230:231]
	v_mov_b64_e32 v[18:19], v[232:233]
	v_pk_mul_f32 v[0:1], v[0:1], v[16:17]
	v_pk_mul_f32 v[2:3], v[2:3], v[18:19]
	v_pk_fma_f32 v[0:1], v[52:53], s[26:27], v[0:1] op_sel_hi:[1,0,1]
	v_pk_fma_f32 v[2:3], v[54:55], s[26:27], v[2:3] op_sel_hi:[1,0,1]
	flat_store_dwordx4 v[76:77], v[0:3] offset:128
	s_nop 1
	v_mov_b64_e32 v[0:1], v[234:235]
	v_mov_b64_e32 v[2:3], v[236:237]
	v_pk_mul_f32 v[0:1], v[4:5], v[0:1]
	v_pk_mul_f32 v[2:3], v[6:7], v[2:3]
	v_pk_fma_f32 v[0:1], v[56:57], s[26:27], v[0:1] op_sel_hi:[1,0,1]
	v_pk_fma_f32 v[2:3], v[58:59], s[26:27], v[2:3] op_sel_hi:[1,0,1]
	flat_store_dwordx4 v[76:77], v[0:3] offset:160
	s_nop 1
	v_mov_b64_e32 v[0:1], v[238:239]
	v_mov_b64_e32 v[2:3], v[240:241]
	v_pk_mul_f32 v[0:1], v[8:9], v[0:1]
	v_pk_mul_f32 v[2:3], v[10:11], v[2:3]
	v_pk_fma_f32 v[0:1], v[60:61], s[26:27], v[0:1] op_sel_hi:[1,0,1]
	v_pk_fma_f32 v[2:3], v[62:63], s[26:27], v[2:3] op_sel_hi:[1,0,1]
	flat_store_dwordx4 v[76:77], v[0:3] offset:192
	s_nop 1
	v_mov_b64_e32 v[0:1], v[242:243]
	v_mov_b64_e32 v[2:3], v[244:245]
	v_pk_mul_f32 v[0:1], v[12:13], v[0:1]
	v_pk_mul_f32 v[2:3], v[14:15], v[2:3]
	v_pk_fma_f32 v[0:1], v[72:73], s[26:27], v[0:1] op_sel_hi:[1,0,1]
	v_pk_fma_f32 v[2:3], v[74:75], s[26:27], v[2:3] op_sel_hi:[1,0,1]
	flat_store_dwordx4 v[76:77], v[0:3] offset:224
	global_load_dwordx4 v[70:73], v[190:191], off
	s_nop 0
	global_load_dwordx4 v[74:77], v[192:193], off
	global_load_dwordx4 v[98:101], v[160:161], off
	global_load_dwordx4 v[78:81], v[162:163], off
	global_load_dwordx4 v[82:85], v[164:165], off
	global_load_dwordx4 v[86:89], v[166:167], off
	global_load_dwordx4 v[90:93], v[168:169], off
	global_load_dwordx4 v[94:97], v[170:171], off
	global_load_dwordx4 v[102:105], v[172:173], off
	global_load_dwordx4 v[106:109], v[174:175], off
	v_mov_b32_e32 v0, 0
	v_mov_b64_e32 v[190:191], v[182:183]
	v_mov_b32_e32 v1, v0
	v_mov_b32_e32 v2, v0
	v_mov_b32_e32 v3, v0
	v_mov_b32_e32 v4, v0
	v_mov_b32_e32 v5, v0
	v_mov_b32_e32 v6, v0
	v_mov_b32_e32 v7, v0
	v_mov_b32_e32 v8, v0
	v_mov_b32_e32 v9, v0
	v_mov_b32_e32 v10, v0
	v_mov_b32_e32 v11, v0
	v_mov_b32_e32 v12, v0
	v_mov_b32_e32 v13, v0
	v_mov_b32_e32 v14, v0
	v_mov_b32_e32 v15, v0
	v_mov_b32_e32 v16, v0
	v_mov_b32_e32 v17, v0
	v_mov_b32_e32 v18, v0
	v_mov_b32_e32 v19, v0
	v_mov_b32_e32 v20, v0
	v_mov_b32_e32 v21, v0
	v_mov_b32_e32 v22, v0
	v_mov_b32_e32 v23, v0
	v_mov_b32_e32 v24, v0
	v_mov_b32_e32 v25, v0
	v_mov_b32_e32 v26, v0
	v_mov_b32_e32 v27, v0
	v_mov_b32_e32 v28, v0
	v_mov_b32_e32 v29, v0
	v_mov_b32_e32 v30, v0
	v_mov_b32_e32 v31, v0
	v_mov_b32_e32 v32, v0
	v_mov_b32_e32 v33, v0
	v_mov_b32_e32 v34, v0
	v_mov_b32_e32 v35, v0
	v_mov_b32_e32 v36, v0
	v_mov_b32_e32 v37, v0
	v_mov_b32_e32 v38, v0
	v_mov_b32_e32 v39, v0
	v_mov_b32_e32 v40, v0
	v_mov_b32_e32 v41, v0
	v_mov_b32_e32 v42, v0
	v_mov_b32_e32 v43, v0
	v_mov_b32_e32 v44, v0
	v_mov_b32_e32 v45, v0
	v_mov_b32_e32 v46, v0
	v_mov_b32_e32 v47, v0
	v_mov_b32_e32 v48, v0
	v_mov_b32_e32 v49, v0
	v_mov_b32_e32 v50, v0
	v_mov_b32_e32 v51, v0
	v_mov_b32_e32 v52, v0
	v_mov_b32_e32 v53, v0
	v_mov_b32_e32 v54, v0
	v_mov_b32_e32 v55, v0
	v_mov_b32_e32 v56, v0
	v_mov_b32_e32 v57, v0
	v_mov_b32_e32 v58, v0
	v_mov_b32_e32 v59, v0
	v_mov_b32_e32 v60, v0
	v_mov_b32_e32 v61, v0
	v_mov_b32_e32 v62, v0
	v_mov_b32_e32 v63, v0
	s_branch .LBB0_1045

.LBB0_1045:
	s_cmpk_gt_u32 s3, 0x3bf
	s_cselect_b64 s[38:39], -1, 0
	s_and_b64 vcc, exec, s[38:39]
	s_waitcnt lgkmcnt(0)
	s_barrier
	s_cbranch_vccnz .Lp4_lastk_0
	v_lshl_add_u64 v[242:243], v[190:191], 0, s[8:9]
	s_waitcnt vmcnt(9)
	ds_write_b128 v189, v[70:73]
	s_nop 0
	v_add_co_u32_e32 v70, vcc, 0x80000, v242
	s_nop 1
	v_addc_co_u32_e32 v71, vcc, 0, v243, vcc
	global_load_dwordx4 v[70:73], v[70:71], off
	s_waitcnt vmcnt(9)
	ds_write_b128 v189, v[74:77] offset:4608
	s_nop 0
	v_add_co_u32_e32 v74, vcc, 0x90000, v242
	s_nop 1
	v_addc_co_u32_e32 v75, vcc, 0, v243, vcc
	global_load_dwordx4 v[74:77], v[74:75], off
	s_waitcnt vmcnt(9)
	ds_write_b128 v189, v[98:101] offset:9216
	s_nop 0
	global_load_dwordx4 v[98:101], v[190:191], off
	s_waitcnt vmcnt(9)
	ds_write_b128 v189, v[78:81] offset:13824
	s_nop 0
	v_add_co_u32_e32 v78, vcc, 0x10000, v190
	s_nop 1
	v_addc_co_u32_e32 v79, vcc, 0, v191, vcc
	global_load_dwordx4 v[78:81], v[78:79], off
	s_waitcnt vmcnt(9)
	ds_write_b128 v189, v[82:85] offset:18432
	s_nop 0
	v_add_co_u32_e32 v82, vcc, 0x20000, v190
	s_nop 1
	v_addc_co_u32_e32 v83, vcc, 0, v191, vcc
	global_load_dwordx4 v[82:85], v[82:83], off
	s_waitcnt vmcnt(9)
	ds_write_b128 v189, v[86:89] offset:23040
	s_nop 0
	v_add_co_u32_e32 v86, vcc, 0x30000, v190
	s_nop 1
	v_addc_co_u32_e32 v87, vcc, 0, v191, vcc
	global_load_dwordx4 v[86:89], v[86:87], off
	s_waitcnt vmcnt(9)
	ds_write_b128 v189, v[90:93] offset:27648
	s_nop 0
	v_add_co_u32_e32 v90, vcc, s33, v190
	s_nop 1
	v_addc_co_u32_e32 v91, vcc, 0, v191, vcc
	global_load_dwordx4 v[90:93], v[90:91], off
	s_waitcnt vmcnt(9)
	ds_write_b128 v189, v[94:97] offset:32256
	s_nop 0
	v_add_co_u32_e32 v94, vcc, 0x50000, v190
	s_nop 1
	v_addc_co_u32_e32 v95, vcc, 0, v191, vcc
	global_load_dwordx4 v[94:97], v[94:95], off
	s_waitcnt vmcnt(9)
	ds_write_b128 v189, v[102:105] offset:36864
	s_nop 0
	v_add_co_u32_e32 v102, vcc, 0x60000, v190
	s_nop 1
	v_addc_co_u32_e32 v103, vcc, 0, v191, vcc
	global_load_dwordx4 v[102:105], v[102:103], off
	s_waitcnt vmcnt(9)
	ds_write_b128 v189, v[106:109] offset:41472
	s_nop 0
	v_add_co_u32_e32 v106, vcc, 0x70000, v190
	s_nop 1
	v_addc_co_u32_e32 v107, vcc, 0, v191, vcc
	global_load_dwordx4 v[106:109], v[106:107], off
	s_waitcnt lgkmcnt(0)
	s_barrier
	s_branch .LBB0_1044
